# same one-wait batching applied to the second copy of the SSD-B staging loop
# baseline (speedup 1.0000x reference)
.LBB0_842:
	v_add_co_u32_e32 v8, vcc, 0x90000, v4
	v_add_u32_e32 v7, 0xfffff000, v6
	s_nop 0
	v_addc_co_u32_e32 v9, vcc, 0, v5, vcc
	global_load_dword v3, v[8:9], off
	global_load_dword v10, v[4:5], off
	v_add_u32_e32 v0, 0x200, v0
	v_cmp_lt_i32_e32 vcc, s4, v0
	s_or_b64 s[22:23], vcc, s[22:23]
	v_lshl_add_u64 v[4:5], v[4:5], 0, s[20:21]
	s_waitcnt vmcnt(0) lgkmcnt(0)
	ds_write_b32 v7, v3
	ds_write_b32 v6, v10
	v_add_u32_e32 v6, 0x800, v6
	s_andn2_b64 exec, exec, s[22:23]
	s_cbranch_execnz .LBB0_842
